# same as previous plus s_sleep 1 in the same-XCD barrier polls
# baseline (speedup 1.0000x reference)
; __device__ __forceinline__ unsigned xb_ld(unsigned* p)              { return __hip_atomic_load(p, __ATOMIC_RELAXED, __HIP_MEMORY_SCOPE_AGENT); }
; __device__ __forceinline__ unsigned xb_add(unsigned* p, unsigned v) { return __hip_atomic_fetch_add(p, v, __ATOMIC_RELAXED, __HIP_MEMORY_SCOPE_AGENT); }
; #define XB_SPIN(cond, bar) do { unsigned _sp = 0; while (cond) { __builtin_amdgcn_s_sleep(1); \
;     if ((++_sp & 255u) == 0u) { if (xb_ld(&(bar)[XB_TMO])) break; if (_sp > XB_SPIN_CAP) { atomicAdd(&(bar)[XB_TMO], 1u); break; } } } } while (0)
; __device__ __forceinline__ void xcd_barrier(const XcdBarrier& b) {
;     ...
;             else XB_SPIN(xb_ld(&bar[XB_TOPGEN]) == tg, bar);
;             __builtin_amdgcn_fence(__ATOMIC_ACQUIRE, "agent");
;             xb_add(&bar[XB_XGEN(b.x)], 1u);
;             asm volatile("s_waitcnt vmcnt(0)" ::: "memory");
;         } else {
;             XB_SPIN(xb_ld(&bar[XB_XGEN(b.x)]) == gen, bar);
.Ltb307_fast:
	global_atomic_add v0, v1, s[8:9]
	buffer_inv sc1
.Ltb307_spin:
	global_load_dword v3, v0, s[8:9] sc1
	s_waitcnt vmcnt(0)
	v_cmp_ge_u32_e32 vcc, v3, v2
	s_cbranch_vccnz .Ltb307_frel
	s_sleep 1
	s_add_u32 s15, s15, 1
	s_cmp_lt_u32 s15, 0x400000
	s_cbranch_scc1 .Ltb307_spin
.Ltb307_frel:
.Ltb307_done:
	s_or_b64 exec, exec, s[4:5]
	s_barrier

; __device__ __forceinline__ unsigned xb_ld(unsigned* p)              { return __hip_atomic_load(p, __ATOMIC_RELAXED, __HIP_MEMORY_SCOPE_AGENT); }
; __device__ __forceinline__ unsigned xb_add(unsigned* p, unsigned v) { return __hip_atomic_fetch_add(p, v, __ATOMIC_RELAXED, __HIP_MEMORY_SCOPE_AGENT); }
; #define XB_SPIN(cond, bar) do { unsigned _sp = 0; while (cond) { __builtin_amdgcn_s_sleep(1); \
;     if ((++_sp & 255u) == 0u) { if (xb_ld(&(bar)[XB_TMO])) break; if (_sp > XB_SPIN_CAP) { atomicAdd(&(bar)[XB_TMO], 1u); break; } } } } while (0)
; __device__ __forceinline__ void xcd_barrier(const XcdBarrier& b) {
;     ...
;             else XB_SPIN(xb_ld(&bar[XB_TOPGEN]) == tg, bar);
;             __builtin_amdgcn_fence(__ATOMIC_ACQUIRE, "agent");
;             xb_add(&bar[XB_XGEN(b.x)], 1u);
;             asm volatile("s_waitcnt vmcnt(0)" ::: "memory");
;         } else {
;             XB_SPIN(xb_ld(&bar[XB_XGEN(b.x)]) == gen, bar);
.Ltb386_fast:
	global_atomic_add v0, v1, s[8:9]
	buffer_inv sc1
.Ltb386_spin:
	global_load_dword v3, v0, s[8:9] sc1
	s_waitcnt vmcnt(0)
	v_cmp_ge_u32_e32 vcc, v3, v2
	s_cbranch_vccnz .Ltb386_frel
	s_sleep 1
	s_add_u32 s15, s15, 1
	s_cmp_lt_u32 s15, 0x400000
	s_cbranch_scc1 .Ltb386_spin
.Ltb386_frel:
.Ltb386_done:
	s_or_b64 exec, exec, s[4:5]
	s_barrier

; __device__ __forceinline__ unsigned xb_ld(unsigned* p)              { return __hip_atomic_load(p, __ATOMIC_RELAXED, __HIP_MEMORY_SCOPE_AGENT); }
; __device__ __forceinline__ unsigned xb_add(unsigned* p, unsigned v) { return __hip_atomic_fetch_add(p, v, __ATOMIC_RELAXED, __HIP_MEMORY_SCOPE_AGENT); }
; #define XB_SPIN(cond, bar) do { unsigned _sp = 0; while (cond) { __builtin_amdgcn_s_sleep(1); \
;     if ((++_sp & 255u) == 0u) { if (xb_ld(&(bar)[XB_TMO])) break; if (_sp > XB_SPIN_CAP) { atomicAdd(&(bar)[XB_TMO], 1u); break; } } } } while (0)
; __device__ __forceinline__ void xcd_barrier(const XcdBarrier& b) {
;     ...
;             else XB_SPIN(xb_ld(&bar[XB_TOPGEN]) == tg, bar);
;             __builtin_amdgcn_fence(__ATOMIC_ACQUIRE, "agent");
;             xb_add(&bar[XB_XGEN(b.x)], 1u);
;             asm volatile("s_waitcnt vmcnt(0)" ::: "memory");
;         } else {
;             XB_SPIN(xb_ld(&bar[XB_XGEN(b.x)]) == gen, bar);
.Ltb482_fast:
	global_atomic_add v0, v1, s[8:9]
	buffer_inv sc1
.Ltb482_spin:
	global_load_dword v3, v0, s[8:9] sc1
	s_waitcnt vmcnt(0)
	v_cmp_ge_u32_e32 vcc, v3, v2
	s_cbranch_vccnz .Ltb482_frel
	s_sleep 1
	s_add_u32 s15, s15, 1
	s_cmp_lt_u32 s15, 0x400000
	s_cbranch_scc1 .Ltb482_spin

; __device__ __forceinline__ unsigned xb_ld(unsigned* p)              { return __hip_atomic_load(p, __ATOMIC_RELAXED, __HIP_MEMORY_SCOPE_AGENT); }
; __device__ __forceinline__ unsigned xb_add(unsigned* p, unsigned v) { return __hip_atomic_fetch_add(p, v, __ATOMIC_RELAXED, __HIP_MEMORY_SCOPE_AGENT); }
; #define XB_SPIN(cond, bar) do { unsigned _sp = 0; while (cond) { __builtin_amdgcn_s_sleep(1); \
;     if ((++_sp & 255u) == 0u) { if (xb_ld(&(bar)[XB_TMO])) break; if (_sp > XB_SPIN_CAP) { atomicAdd(&(bar)[XB_TMO], 1u); break; } } } } while (0)
; __device__ __forceinline__ void xcd_barrier(const XcdBarrier& b) {
;     ...
;     if (threadIdx.x == 0) {
;         unsigned* bar = b.bar;
;         __builtin_amdgcn_s_waitcnt(0);
;         unsigned nloc = b.st[0], nx = b.st[1];
;         if (nloc == 0u) { xcd_barrier_complete(bar, b.x, nloc, nx); b.st[0] = nloc; b.st[1] = nx; }
;         const unsigned old = xb_add(&bar[XB_XSUB(b.x)], 1u);
;         const unsigned gen = old / nloc;
;         if (old + 1u == (gen + 1u) * nloc) {
;             __builtin_amdgcn_fence(__ATOMIC_RELEASE, "agent");
;             asm volatile("s_waitcnt vmcnt(0)" ::: "memory");
;             const unsigned og = xb_add(&bar[XB_TOP], 1u);
;             const unsigned tg = og / nx;
;             if (og + 1u == (tg + 1u) * nx) xb_add(&bar[XB_TOPGEN], 1u);
;             else XB_SPIN(xb_ld(&bar[XB_TOPGEN]) == tg, bar);
;             __builtin_amdgcn_fence(__ATOMIC_ACQUIRE, "agent");
;             xb_add(&bar[XB_XGEN(b.x)], 1u);
;             asm volatile("s_waitcnt vmcnt(0)" ::: "memory");
;         } else {
;             XB_SPIN(xb_ld(&bar[XB_XGEN(b.x)]) == gen, bar);
;             __builtin_amdgcn_fence(__ATOMIC_ACQUIRE, "agent");
;             asm volatile("s_waitcnt vmcnt(0)" ::: "memory");
;         }
;     }
;     __syncthreads();
.Ltb675_fast:
	global_atomic_add v0, v1, s[8:9]
	buffer_inv sc1
.Ltb675_spin:
	global_load_dword v3, v0, s[8:9] sc1
	s_waitcnt vmcnt(0)
	v_cmp_ge_u32_e32 vcc, v3, v2
	s_cbranch_vccnz .Ltb675_frel
	s_sleep 1
	s_add_u32 s15, s15, 1
	s_cmp_lt_u32 s15, 0x400000
	s_cbranch_scc1 .Ltb675_spin

; __device__ __forceinline__ unsigned xb_ld(unsigned* p)              { return __hip_atomic_load(p, __ATOMIC_RELAXED, __HIP_MEMORY_SCOPE_AGENT); }
; __device__ __forceinline__ unsigned xb_add(unsigned* p, unsigned v) { return __hip_atomic_fetch_add(p, v, __ATOMIC_RELAXED, __HIP_MEMORY_SCOPE_AGENT); }
; #define XB_SPIN(cond, bar) do { unsigned _sp = 0; while (cond) { __builtin_amdgcn_s_sleep(1); \
;     if ((++_sp & 255u) == 0u) { if (xb_ld(&(bar)[XB_TMO])) break; if (_sp > XB_SPIN_CAP) { atomicAdd(&(bar)[XB_TMO], 1u); break; } } } } while (0)
; __device__ __forceinline__ void xcd_barrier(const XcdBarrier& b) {
;     ...
;     if (threadIdx.x == 0) {
;         unsigned* bar = b.bar;
;         __builtin_amdgcn_s_waitcnt(0);
;         unsigned nloc = b.st[0], nx = b.st[1];
;         if (nloc == 0u) { xcd_barrier_complete(bar, b.x, nloc, nx); b.st[0] = nloc; b.st[1] = nx; }
;         const unsigned old = xb_add(&bar[XB_XSUB(b.x)], 1u);
;         const unsigned gen = old / nloc;
;         if (old + 1u == (gen + 1u) * nloc) {
;             __builtin_amdgcn_fence(__ATOMIC_RELEASE, "agent");
;             asm volatile("s_waitcnt vmcnt(0)" ::: "memory");
;             const unsigned og = xb_add(&bar[XB_TOP], 1u);
;             const unsigned tg = og / nx;
;             if (og + 1u == (tg + 1u) * nx) xb_add(&bar[XB_TOPGEN], 1u);
;             else XB_SPIN(xb_ld(&bar[XB_TOPGEN]) == tg, bar);
;             __builtin_amdgcn_fence(__ATOMIC_ACQUIRE, "agent");
;             xb_add(&bar[XB_XGEN(b.x)], 1u);
;             asm volatile("s_waitcnt vmcnt(0)" ::: "memory");
;         } else {
;             XB_SPIN(xb_ld(&bar[XB_XGEN(b.x)]) == gen, bar);
;             __builtin_amdgcn_fence(__ATOMIC_ACQUIRE, "agent");
;             asm volatile("s_waitcnt vmcnt(0)" ::: "memory");
;         }
;     }
;     __syncthreads();
.Ltb675_fnbs:
	global_load_dword v3, v0, s[8:9] sc1
	s_waitcnt vmcnt(0)
	v_cmp_ge_u32_e32 vcc, v3, v2
	s_cbranch_vccnz .Ltb675_fnbd
	s_sleep 1
	s_add_u32 s15, s15, 1
	s_cmp_lt_u32 s15, 0x400000
	s_cbranch_scc1 .Ltb675_fnbs
.Ltb675_fnbd:
.Ltb675_done:
	s_or_b64 exec, exec, s[4:5]
	s_barrier

; __device__ __forceinline__ unsigned xb_ld(unsigned* p)              { return __hip_atomic_load(p, __ATOMIC_RELAXED, __HIP_MEMORY_SCOPE_AGENT); }
; __device__ __forceinline__ unsigned xb_add(unsigned* p, unsigned v) { return __hip_atomic_fetch_add(p, v, __ATOMIC_RELAXED, __HIP_MEMORY_SCOPE_AGENT); }
; #define XB_SPIN(cond, bar) do { unsigned _sp = 0; while (cond) { __builtin_amdgcn_s_sleep(1); \
;     if ((++_sp & 255u) == 0u) { if (xb_ld(&(bar)[XB_TMO])) break; if (_sp > XB_SPIN_CAP) { atomicAdd(&(bar)[XB_TMO], 1u); break; } } } } while (0)
; __device__ __forceinline__ void xcd_barrier(const XcdBarrier& b) {
;     ...
;     if (threadIdx.x == 0) {
;         unsigned* bar = b.bar;
;         __builtin_amdgcn_s_waitcnt(0);
;         unsigned nloc = b.st[0], nx = b.st[1];
;         if (nloc == 0u) { xcd_barrier_complete(bar, b.x, nloc, nx); b.st[0] = nloc; b.st[1] = nx; }
;         const unsigned old = xb_add(&bar[XB_XSUB(b.x)], 1u);
;         const unsigned gen = old / nloc;
;         if (old + 1u == (gen + 1u) * nloc) {
;             __builtin_amdgcn_fence(__ATOMIC_RELEASE, "agent");
;             asm volatile("s_waitcnt vmcnt(0)" ::: "memory");
;             const unsigned og = xb_add(&bar[XB_TOP], 1u);
;             const unsigned tg = og / nx;
;             if (og + 1u == (tg + 1u) * nx) xb_add(&bar[XB_TOPGEN], 1u);
;             else XB_SPIN(xb_ld(&bar[XB_TOPGEN]) == tg, bar);
;             __builtin_amdgcn_fence(__ATOMIC_ACQUIRE, "agent");
;             xb_add(&bar[XB_XGEN(b.x)], 1u);
;             asm volatile("s_waitcnt vmcnt(0)" ::: "memory");
;         } else {
;             XB_SPIN(xb_ld(&bar[XB_XGEN(b.x)]) == gen, bar);
;             __builtin_amdgcn_fence(__ATOMIC_ACQUIRE, "agent");
;             asm volatile("s_waitcnt vmcnt(0)" ::: "memory");
;         }
;     }
;     __syncthreads();
.Ltb769_fast:
	global_atomic_add v0, v1, s[8:9]
	buffer_inv sc1
.Ltb769_spin:
	global_load_dword v3, v0, s[8:9] sc1
	s_waitcnt vmcnt(0)
	v_cmp_ge_u32_e32 vcc, v3, v2
	s_cbranch_vccnz .Ltb769_frel
	s_sleep 1
	s_add_u32 s15, s15, 1
	s_cmp_lt_u32 s15, 0x400000
	s_cbranch_scc1 .Ltb769_spin
.Ltb769_frel:
.Ltb769_done:
	s_or_b64 exec, exec, s[4:5]
	s_barrier

; __device__ __forceinline__ unsigned xb_ld(unsigned* p)              { return __hip_atomic_load(p, __ATOMIC_RELAXED, __HIP_MEMORY_SCOPE_AGENT); }
; __device__ __forceinline__ unsigned xb_add(unsigned* p, unsigned v) { return __hip_atomic_fetch_add(p, v, __ATOMIC_RELAXED, __HIP_MEMORY_SCOPE_AGENT); }
; #define XB_SPIN(cond, bar) do { unsigned _sp = 0; while (cond) { __builtin_amdgcn_s_sleep(1); \
;     if ((++_sp & 255u) == 0u) { if (xb_ld(&(bar)[XB_TMO])) break; if (_sp > XB_SPIN_CAP) { atomicAdd(&(bar)[XB_TMO], 1u); break; } } } } while (0)
; __device__ __forceinline__ void xcd_barrier(const XcdBarrier& b) {
;     ...
;     if (threadIdx.x == 0) {
;         unsigned* bar = b.bar;
;         __builtin_amdgcn_s_waitcnt(0);
;         unsigned nloc = b.st[0], nx = b.st[1];
;         if (nloc == 0u) { xcd_barrier_complete(bar, b.x, nloc, nx); b.st[0] = nloc; b.st[1] = nx; }
;         const unsigned old = xb_add(&bar[XB_XSUB(b.x)], 1u);
;         const unsigned gen = old / nloc;
;         if (old + 1u == (gen + 1u) * nloc) {
;             __builtin_amdgcn_fence(__ATOMIC_RELEASE, "agent");
;             asm volatile("s_waitcnt vmcnt(0)" ::: "memory");
;             const unsigned og = xb_add(&bar[XB_TOP], 1u);
;             const unsigned tg = og / nx;
;             if (og + 1u == (tg + 1u) * nx) xb_add(&bar[XB_TOPGEN], 1u);
;             else XB_SPIN(xb_ld(&bar[XB_TOPGEN]) == tg, bar);
;             __builtin_amdgcn_fence(__ATOMIC_ACQUIRE, "agent");
;             xb_add(&bar[XB_XGEN(b.x)], 1u);
;             asm volatile("s_waitcnt vmcnt(0)" ::: "memory");
;         } else {
;             XB_SPIN(xb_ld(&bar[XB_XGEN(b.x)]) == gen, bar);
;             __builtin_amdgcn_fence(__ATOMIC_ACQUIRE, "agent");
;             asm volatile("s_waitcnt vmcnt(0)" ::: "memory");
;         }
;     }
;     __syncthreads();
.Ltb868_fast:
	global_atomic_add v0, v1, s[8:9]
	buffer_inv sc1
.Ltb868_spin:
	global_load_dword v3, v0, s[8:9] sc1
	s_waitcnt vmcnt(0)
	v_cmp_ge_u32_e32 vcc, v3, v2
	s_cbranch_vccnz .Ltb868_frel
	s_sleep 1
	s_add_u32 s15, s15, 1
	s_cmp_lt_u32 s15, 0x400000
	s_cbranch_scc1 .Ltb868_spin
.Ltb868_frel:
.Ltb868_done:
	s_or_b64 exec, exec, s[4:5]
	s_barrier

; __device__ __forceinline__ unsigned xb_ld(unsigned* p)              { return __hip_atomic_load(p, __ATOMIC_RELAXED, __HIP_MEMORY_SCOPE_AGENT); }
; __device__ __forceinline__ unsigned xb_add(unsigned* p, unsigned v) { return __hip_atomic_fetch_add(p, v, __ATOMIC_RELAXED, __HIP_MEMORY_SCOPE_AGENT); }
; #define XB_SPIN(cond, bar) do { unsigned _sp = 0; while (cond) { __builtin_amdgcn_s_sleep(1); \
;     if ((++_sp & 255u) == 0u) { if (xb_ld(&(bar)[XB_TMO])) break; if (_sp > XB_SPIN_CAP) { atomicAdd(&(bar)[XB_TMO], 1u); break; } } } } while (0)
; __device__ __forceinline__ void xcd_barrier(const XcdBarrier& b) {
;     ...
;     if (threadIdx.x == 0) {
;         unsigned* bar = b.bar;
;         __builtin_amdgcn_s_waitcnt(0);
;         unsigned nloc = b.st[0], nx = b.st[1];
;         if (nloc == 0u) { xcd_barrier_complete(bar, b.x, nloc, nx); b.st[0] = nloc; b.st[1] = nx; }
;         const unsigned old = xb_add(&bar[XB_XSUB(b.x)], 1u);
;         const unsigned gen = old / nloc;
;         if (old + 1u == (gen + 1u) * nloc) {
;             __builtin_amdgcn_fence(__ATOMIC_RELEASE, "agent");
;             asm volatile("s_waitcnt vmcnt(0)" ::: "memory");
;             const unsigned og = xb_add(&bar[XB_TOP], 1u);
;             const unsigned tg = og / nx;
;             if (og + 1u == (tg + 1u) * nx) xb_add(&bar[XB_TOPGEN], 1u);
;             else XB_SPIN(xb_ld(&bar[XB_TOPGEN]) == tg, bar);
;             __builtin_amdgcn_fence(__ATOMIC_ACQUIRE, "agent");
;             xb_add(&bar[XB_XGEN(b.x)], 1u);
;             asm volatile("s_waitcnt vmcnt(0)" ::: "memory");
;         } else {
;             XB_SPIN(xb_ld(&bar[XB_XGEN(b.x)]) == gen, bar);
;             __builtin_amdgcn_fence(__ATOMIC_ACQUIRE, "agent");
;             asm volatile("s_waitcnt vmcnt(0)" ::: "memory");
;         }
;     }
;     __syncthreads();
.Ltb943_fast:
	global_atomic_add v0, v1, s[8:9]
	buffer_inv sc1
.Ltb943_spin:
	global_load_dword v3, v0, s[8:9] sc1
	s_waitcnt vmcnt(0)
	v_cmp_ge_u32_e32 vcc, v3, v2
	s_cbranch_vccnz .Ltb943_frel
	s_sleep 1
	s_add_u32 s15, s15, 1
	s_cmp_lt_u32 s15, 0x400000
	s_cbranch_scc1 .Ltb943_spin
.Ltb943_frel:
.Ltb943_done:
	s_or_b64 exec, exec, s[4:5]
	s_barrier

; __device__ __forceinline__ unsigned xb_ld(unsigned* p)              { return __hip_atomic_load(p, __ATOMIC_RELAXED, __HIP_MEMORY_SCOPE_AGENT); }
; __device__ __forceinline__ unsigned xb_add(unsigned* p, unsigned v) { return __hip_atomic_fetch_add(p, v, __ATOMIC_RELAXED, __HIP_MEMORY_SCOPE_AGENT); }
; #define XB_SPIN(cond, bar) do { unsigned _sp = 0; while (cond) { __builtin_amdgcn_s_sleep(1); \
;     if ((++_sp & 255u) == 0u) { if (xb_ld(&(bar)[XB_TMO])) break; if (_sp > XB_SPIN_CAP) { atomicAdd(&(bar)[XB_TMO], 1u); break; } } } } while (0)
; __device__ __forceinline__ void xcd_barrier(const XcdBarrier& b) {
;     ...
;     if (threadIdx.x == 0) {
;         unsigned* bar = b.bar;
;         __builtin_amdgcn_s_waitcnt(0);
;         unsigned nloc = b.st[0], nx = b.st[1];
;         if (nloc == 0u) { xcd_barrier_complete(bar, b.x, nloc, nx); b.st[0] = nloc; b.st[1] = nx; }
;         const unsigned old = xb_add(&bar[XB_XSUB(b.x)], 1u);
;         const unsigned gen = old / nloc;
;         if (old + 1u == (gen + 1u) * nloc) {
;             __builtin_amdgcn_fence(__ATOMIC_RELEASE, "agent");
;             asm volatile("s_waitcnt vmcnt(0)" ::: "memory");
;             const unsigned og = xb_add(&bar[XB_TOP], 1u);
;             const unsigned tg = og / nx;
;             if (og + 1u == (tg + 1u) * nx) xb_add(&bar[XB_TOPGEN], 1u);
;             else XB_SPIN(xb_ld(&bar[XB_TOPGEN]) == tg, bar);
;             __builtin_amdgcn_fence(__ATOMIC_ACQUIRE, "agent");
;             xb_add(&bar[XB_XGEN(b.x)], 1u);
;             asm volatile("s_waitcnt vmcnt(0)" ::: "memory");
;         } else {
;             XB_SPIN(xb_ld(&bar[XB_XGEN(b.x)]) == gen, bar);
;             __builtin_amdgcn_fence(__ATOMIC_ACQUIRE, "agent");
;             asm volatile("s_waitcnt vmcnt(0)" ::: "memory");
;         }
;     }
;     __syncthreads();
.Ltb1039_fast:
	global_atomic_add v0, v1, s[8:9]
	buffer_inv sc1
.Ltb1039_spin:
	global_load_dword v3, v0, s[8:9] sc1
	s_waitcnt vmcnt(0)
	v_cmp_ge_u32_e32 vcc, v3, v2
	s_cbranch_vccnz .Ltb1039_frel
	s_sleep 1
	s_add_u32 s15, s15, 1
	s_cmp_lt_u32 s15, 0x400000
	s_cbranch_scc1 .Ltb1039_spin

; __device__ __forceinline__ unsigned xb_ld(unsigned* p)              { return __hip_atomic_load(p, __ATOMIC_RELAXED, __HIP_MEMORY_SCOPE_AGENT); }
; __device__ __forceinline__ unsigned xb_add(unsigned* p, unsigned v) { return __hip_atomic_fetch_add(p, v, __ATOMIC_RELAXED, __HIP_MEMORY_SCOPE_AGENT); }
; #define XB_SPIN(cond, bar) do { unsigned _sp = 0; while (cond) { __builtin_amdgcn_s_sleep(1); \
;     if ((++_sp & 255u) == 0u) { if (xb_ld(&(bar)[XB_TMO])) break; if (_sp > XB_SPIN_CAP) { atomicAdd(&(bar)[XB_TMO], 1u); break; } } } } while (0)
; __device__ __forceinline__ void xcd_barrier(const XcdBarrier& b) {
;     ...
;     if (threadIdx.x == 0) {
;         unsigned* bar = b.bar;
;         __builtin_amdgcn_s_waitcnt(0);
;         unsigned nloc = b.st[0], nx = b.st[1];
;         if (nloc == 0u) { xcd_barrier_complete(bar, b.x, nloc, nx); b.st[0] = nloc; b.st[1] = nx; }
;         const unsigned old = xb_add(&bar[XB_XSUB(b.x)], 1u);
;         const unsigned gen = old / nloc;
;         if (old + 1u == (gen + 1u) * nloc) {
;             __builtin_amdgcn_fence(__ATOMIC_RELEASE, "agent");
;             asm volatile("s_waitcnt vmcnt(0)" ::: "memory");
;             const unsigned og = xb_add(&bar[XB_TOP], 1u);
;             const unsigned tg = og / nx;
;             if (og + 1u == (tg + 1u) * nx) xb_add(&bar[XB_TOPGEN], 1u);
;             else XB_SPIN(xb_ld(&bar[XB_TOPGEN]) == tg, bar);
;             __builtin_amdgcn_fence(__ATOMIC_ACQUIRE, "agent");
;             xb_add(&bar[XB_XGEN(b.x)], 1u);
;             asm volatile("s_waitcnt vmcnt(0)" ::: "memory");
;         } else {
;             XB_SPIN(xb_ld(&bar[XB_XGEN(b.x)]) == gen, bar);
;             __builtin_amdgcn_fence(__ATOMIC_ACQUIRE, "agent");
;             asm volatile("s_waitcnt vmcnt(0)" ::: "memory");
;         }
;     }
;     __syncthreads();
.Ltb1134_fast:
	global_atomic_add v0, v1, s[8:9]
	buffer_inv sc1
.Ltb1134_spin:
	global_load_dword v3, v0, s[8:9] sc1
	s_waitcnt vmcnt(0)
	v_cmp_ge_u32_e32 vcc, v3, v2
	s_cbranch_vccnz .Ltb1134_frel
	s_sleep 1
	s_add_u32 s15, s15, 1
	s_cmp_lt_u32 s15, 0x400000
	s_cbranch_scc1 .Ltb1134_spin
.Ltb1134_frel:
.Ltb1134_done:
	s_or_b64 exec, exec, s[4:5]
	s_barrier

; __device__ __forceinline__ unsigned xb_ld(unsigned* p)              { return __hip_atomic_load(p, __ATOMIC_RELAXED, __HIP_MEMORY_SCOPE_AGENT); }
; __device__ __forceinline__ unsigned xb_add(unsigned* p, unsigned v) { return __hip_atomic_fetch_add(p, v, __ATOMIC_RELAXED, __HIP_MEMORY_SCOPE_AGENT); }
; #define XB_SPIN(cond, bar) do { unsigned _sp = 0; while (cond) { __builtin_amdgcn_s_sleep(1); \
;     if ((++_sp & 255u) == 0u) { if (xb_ld(&(bar)[XB_TMO])) break; if (_sp > XB_SPIN_CAP) { atomicAdd(&(bar)[XB_TMO], 1u); break; } } } } while (0)
; __device__ __forceinline__ void xcd_barrier(const XcdBarrier& b) {
;     ...
;     if (threadIdx.x == 0) {
;         unsigned* bar = b.bar;
;         __builtin_amdgcn_s_waitcnt(0);
;         unsigned nloc = b.st[0], nx = b.st[1];
;         if (nloc == 0u) { xcd_barrier_complete(bar, b.x, nloc, nx); b.st[0] = nloc; b.st[1] = nx; }
;         const unsigned old = xb_add(&bar[XB_XSUB(b.x)], 1u);
;         const unsigned gen = old / nloc;
;         if (old + 1u == (gen + 1u) * nloc) {
;             __builtin_amdgcn_fence(__ATOMIC_RELEASE, "agent");
;             asm volatile("s_waitcnt vmcnt(0)" ::: "memory");
;             const unsigned og = xb_add(&bar[XB_TOP], 1u);
;             const unsigned tg = og / nx;
;             if (og + 1u == (tg + 1u) * nx) xb_add(&bar[XB_TOPGEN], 1u);
;             else XB_SPIN(xb_ld(&bar[XB_TOPGEN]) == tg, bar);
;             __builtin_amdgcn_fence(__ATOMIC_ACQUIRE, "agent");
;             xb_add(&bar[XB_XGEN(b.x)], 1u);
;             asm volatile("s_waitcnt vmcnt(0)" ::: "memory");
;         } else {
;             XB_SPIN(xb_ld(&bar[XB_XGEN(b.x)]) == gen, bar);
;             __builtin_amdgcn_fence(__ATOMIC_ACQUIRE, "agent");
;             asm volatile("s_waitcnt vmcnt(0)" ::: "memory");
;         }
;     }
;     __syncthreads();
.Ltb1213_fast:
	global_atomic_add v0, v1, s[8:9]
	buffer_inv sc1
.Ltb1213_spin:
	global_load_dword v3, v0, s[8:9] sc1
	s_waitcnt vmcnt(0)
	v_cmp_ge_u32_e32 vcc, v3, v2
	s_cbranch_vccnz .Ltb1213_frel
	s_sleep 1
	s_add_u32 s15, s15, 1
	s_cmp_lt_u32 s15, 0x400000
	s_cbranch_scc1 .Ltb1213_spin
.Ltb1213_frel:
.Ltb1213_done:
	s_or_b64 exec, exec, s[4:5]
	s_barrier

; __device__ __forceinline__ unsigned xb_ld(unsigned* p)              { return __hip_atomic_load(p, __ATOMIC_RELAXED, __HIP_MEMORY_SCOPE_AGENT); }
; __device__ __forceinline__ unsigned xb_add(unsigned* p, unsigned v) { return __hip_atomic_fetch_add(p, v, __ATOMIC_RELAXED, __HIP_MEMORY_SCOPE_AGENT); }
; #define XB_SPIN(cond, bar) do { unsigned _sp = 0; while (cond) { __builtin_amdgcn_s_sleep(1); \
;     if ((++_sp & 255u) == 0u) { if (xb_ld(&(bar)[XB_TMO])) break; if (_sp > XB_SPIN_CAP) { atomicAdd(&(bar)[XB_TMO], 1u); break; } } } } while (0)
; __device__ __forceinline__ void xcd_barrier(const XcdBarrier& b) {
;     ...
;     if (threadIdx.x == 0) {
;         unsigned* bar = b.bar;
;         __builtin_amdgcn_s_waitcnt(0);
;         unsigned nloc = b.st[0], nx = b.st[1];
;         if (nloc == 0u) { xcd_barrier_complete(bar, b.x, nloc, nx); b.st[0] = nloc; b.st[1] = nx; }
;         const unsigned old = xb_add(&bar[XB_XSUB(b.x)], 1u);
;         const unsigned gen = old / nloc;
;         if (old + 1u == (gen + 1u) * nloc) {
;             __builtin_amdgcn_fence(__ATOMIC_RELEASE, "agent");
;             asm volatile("s_waitcnt vmcnt(0)" ::: "memory");
;             const unsigned og = xb_add(&bar[XB_TOP], 1u);
;             const unsigned tg = og / nx;
;             if (og + 1u == (tg + 1u) * nx) xb_add(&bar[XB_TOPGEN], 1u);
;             else XB_SPIN(xb_ld(&bar[XB_TOPGEN]) == tg, bar);
;             __builtin_amdgcn_fence(__ATOMIC_ACQUIRE, "agent");
;             xb_add(&bar[XB_XGEN(b.x)], 1u);
;             asm volatile("s_waitcnt vmcnt(0)" ::: "memory");
;         } else {
;             XB_SPIN(xb_ld(&bar[XB_XGEN(b.x)]) == gen, bar);
;             __builtin_amdgcn_fence(__ATOMIC_ACQUIRE, "agent");
;             asm volatile("s_waitcnt vmcnt(0)" ::: "memory");
;         }
;     }
;     __syncthreads();
.Ltb1309_fast:
	global_atomic_add v0, v1, s[8:9]
	buffer_inv sc1
.Ltb1309_spin:
	global_load_dword v3, v0, s[8:9] sc1
	s_waitcnt vmcnt(0)
	v_cmp_ge_u32_e32 vcc, v3, v2
	s_cbranch_vccnz .Ltb1309_frel
	s_sleep 1
	s_add_u32 s15, s15, 1
	s_cmp_lt_u32 s15, 0x400000
	s_cbranch_scc1 .Ltb1309_spin

; __device__ __forceinline__ unsigned xb_ld(unsigned* p)              { return __hip_atomic_load(p, __ATOMIC_RELAXED, __HIP_MEMORY_SCOPE_AGENT); }
; __device__ __forceinline__ unsigned xb_add(unsigned* p, unsigned v) { return __hip_atomic_fetch_add(p, v, __ATOMIC_RELAXED, __HIP_MEMORY_SCOPE_AGENT); }
; #define XB_SPIN(cond, bar) do { unsigned _sp = 0; while (cond) { __builtin_amdgcn_s_sleep(1); \
;     if ((++_sp & 255u) == 0u) { if (xb_ld(&(bar)[XB_TMO])) break; if (_sp > XB_SPIN_CAP) { atomicAdd(&(bar)[XB_TMO], 1u); break; } } } } while (0)
; __device__ __forceinline__ void xcd_barrier(const XcdBarrier& b) {
;     ...
;     if (threadIdx.x == 0) {
;         unsigned* bar = b.bar;
;         __builtin_amdgcn_s_waitcnt(0);
;         unsigned nloc = b.st[0], nx = b.st[1];
;         if (nloc == 0u) { xcd_barrier_complete(bar, b.x, nloc, nx); b.st[0] = nloc; b.st[1] = nx; }
;         const unsigned old = xb_add(&bar[XB_XSUB(b.x)], 1u);
;         const unsigned gen = old / nloc;
;         if (old + 1u == (gen + 1u) * nloc) {
;             __builtin_amdgcn_fence(__ATOMIC_RELEASE, "agent");
;             asm volatile("s_waitcnt vmcnt(0)" ::: "memory");
;             const unsigned og = xb_add(&bar[XB_TOP], 1u);
;             const unsigned tg = og / nx;
;             if (og + 1u == (tg + 1u) * nx) xb_add(&bar[XB_TOPGEN], 1u);
;             else XB_SPIN(xb_ld(&bar[XB_TOPGEN]) == tg, bar);
;             __builtin_amdgcn_fence(__ATOMIC_ACQUIRE, "agent");
;             xb_add(&bar[XB_XGEN(b.x)], 1u);
;             asm volatile("s_waitcnt vmcnt(0)" ::: "memory");
;         } else {
;             XB_SPIN(xb_ld(&bar[XB_XGEN(b.x)]) == gen, bar);
;             __builtin_amdgcn_fence(__ATOMIC_ACQUIRE, "agent");
;             asm volatile("s_waitcnt vmcnt(0)" ::: "memory");
;         }
;     }
;     __syncthreads();
.Ltb1446_fast:
	global_atomic_add v0, v1, s[8:9]
	buffer_inv sc1
.Ltb1446_spin:
	global_load_dword v3, v0, s[8:9] sc1
	s_waitcnt vmcnt(0)
	v_cmp_ge_u32_e32 vcc, v3, v2
	s_cbranch_vccnz .Ltb1446_frel
	s_sleep 1
	s_add_u32 s15, s15, 1
	s_cmp_lt_u32 s15, 0x400000
	s_cbranch_scc1 .Ltb1446_spin
.Ltb1446_frel:
.Ltb1446_done:
	s_or_b64 exec, exec, s[4:5]
	s_barrier
